# P1: fifth column tile of even units loaded with two dwordx4 (16 rows x 64 B each) instead of eight dword loads; bf16 pieces scattered into the same LDS fragment image with ds_write_b16
# baseline (speedup 1.0000x reference)
.LBB0_107:
	s_and_b32 s29, s28, 1
	s_bfe_i32 s12, s28, 0x10000
	s_lshr_b32 s8, s28, 1
	s_cmp_eq_u32 s29, 0
	s_cselect_b64 s[14:15], -1, 0
	s_cmp_eq_u32 s29, 1
	s_mul_i32 s13, s8, 0x90
	s_cselect_b64 s[8:9], -1, 0
	s_and_b32 s12, s12, 0x50
	s_add_i32 s12, s12, s13
	s_ashr_i32 s13, s12, 31
	v_lshl_add_u64 v[94:95], s[12:13], 2, v[80:81]
	s_load_dwordx2 s[100:101], s[0:1], 0x38
	v_lshrrev_b32_e32 v204, 4, v162
	v_mul_u32_u24_e32 v204, 0x90000, v204
	v_and_b32_e32 v205, 15, v162
	s_lshl_b32 s98, s12, 2
	v_lshl_add_u32 v206, v205, 2, s98
	v_lshl_add_u32 v207, v205, 4, s98
	v_lshrrev_b32_e32 v208, 2, v162
	v_mul_u32_u24_e32 v208, 0x12000, v208
	v_and_b32_e32 v205, 3, v162
	v_lshl_add_u32 v205, v205, 4, s98
	v_add_u32_e32 v205, v208, v205
	v_add_u32_e32 v208, 0x120000, v205
	v_lshrrev_b32_e32 v209, 5, v162
	v_lshlrev_b32_e32 v209, 8, v209
	v_and_b32_e32 v210, 3, v162
	v_lshl_add_u32 v209, v210, 6, v209
	v_bfe_u32 v210, v162, 2, 3
	v_lshl_add_u32 v209, v210, 1, v209
	v_add_u32_e32 v209, s21, v209
	v_add_u32_e32 v204, v204, v207
	v_and_b32_e32 v206, 15, v162
	v_lshrrev_b32_e32 v207, 2, v206
	v_and_b32_e32 v206, 3, v206
	v_lshlrev_b32_e32 v206, 6, v206
	v_lshl_add_u32 v206, v207, 10, v206
	v_lshrrev_b32_e32 v207, 4, v162
	v_lshl_add_u32 v206, v207, 8, v206
	v_add_u32_e32 v206, s21, v206
	s_mul_i32 s98, s91, 0x240000
	s_waitcnt lgkmcnt(0)
	s_add_u32 s100, s100, s98
	s_addc_u32 s101, s101, 0
	v_cndmask_b32_e64 v3, 0, 1, s[14:15]
	s_mov_b32 s98, s100
	s_mov_b32 s99, s101
	v_cmp_ne_u32_e64 s[8:9], 1, v3
	s_nop 1
	global_load_dwordx4 v[164:167], v204, s[98:99] nt
	s_add_u32 s98, s98, 0x12000
	s_addc_u32 s99, s99, 0
	global_load_dwordx4 v[168:171], v204, s[98:99] nt
	s_add_u32 s98, s98, 0x12000
	s_addc_u32 s99, s99, 0
	global_load_dwordx4 v[172:175], v204, s[98:99] nt
	s_add_u32 s98, s98, 0x12000
	s_addc_u32 s99, s99, 0
	global_load_dwordx4 v[176:179], v204, s[98:99] nt
	s_add_u32 s98, s98, 0x12000
	s_addc_u32 s99, s99, 0
	global_load_dwordx4 v[180:183], v204, s[98:99] nt
	s_add_u32 s98, s98, 0x12000
	s_addc_u32 s99, s99, 0
	global_load_dwordx4 v[184:187], v204, s[98:99] nt
	s_add_u32 s98, s98, 0x12000
	s_addc_u32 s99, s99, 0
	global_load_dwordx4 v[188:191], v204, s[98:99] nt
	s_add_u32 s98, s98, 0x12000
	s_addc_u32 s99, s99, 0
	global_load_dwordx4 v[192:195], v204, s[98:99] nt
	s_and_b64 vcc, exec, s[8:9]
	s_cbranch_vccnz .Lp1_skipE_h
	s_sub_u32 s98, s98, 0x7e000
	s_subb_u32 s99, s99, 0
	global_load_dwordx4 v[196:199], v205, s[98:99] offset:256 nt
	global_load_dwordx4 v[200:203], v208, s[98:99] offset:256 nt
	s_add_u32 s98, s98, 0x7e000
	s_addc_u32 s99, s99, 0

.LBB0_124:
	s_bitcmp1_b32 s13, 0
	s_cselect_b32 s19, 0xa000, 0
	v_add_u32_e32 v141, s19, v98
	v_add_u32_e32 v3, s21, v141
	v_add_u32_e32 v207, s19, v206
	v_add_u32_e32 v210, s19, v209
	s_waitcnt vmcnt(0)
	v_cvt_pk_bf16_f32 v44, v164, v168
	v_cvt_pk_bf16_f32 v45, v172, v176
	v_cvt_pk_bf16_f32 v46, v180, v184
	v_cvt_pk_bf16_f32 v47, v188, v192
	ds_write_b128 v207, v[44:47]
	v_cvt_pk_bf16_f32 v44, v165, v169
	v_cvt_pk_bf16_f32 v45, v173, v177
	v_cvt_pk_bf16_f32 v46, v181, v185
	v_cvt_pk_bf16_f32 v47, v189, v193
	ds_write_b128 v207, v[44:47] offset:16
	v_cvt_pk_bf16_f32 v44, v166, v170
	v_cvt_pk_bf16_f32 v45, v174, v178
	v_cvt_pk_bf16_f32 v46, v182, v186
	v_cvt_pk_bf16_f32 v47, v190, v194
	ds_write_b128 v207, v[44:47] offset:32
	v_cvt_pk_bf16_f32 v44, v167, v171
	v_cvt_pk_bf16_f32 v45, v175, v179
	v_cvt_pk_bf16_f32 v46, v183, v187
	v_cvt_pk_bf16_f32 v47, v191, v195
	ds_write_b128 v207, v[44:47] offset:48
	s_and_b64 vcc, exec, s[8:9]
	s_cbranch_vccnz .LBB0_126
	v_cvt_pk_bf16_f32 v44, v196, v197
	v_cvt_pk_bf16_f32 v45, v198, v199
	v_cvt_pk_bf16_f32 v46, v200, v201
	v_cvt_pk_bf16_f32 v47, v202, v203
	ds_write_b16 v210, v44 offset:4096
	ds_write_b16_d16_hi v210, v44 offset:4112
	ds_write_b16 v210, v45 offset:4128
	ds_write_b16_d16_hi v210, v45 offset:4144
	ds_write_b16 v210, v46 offset:4608
	ds_write_b16_d16_hi v210, v46 offset:4624
	ds_write_b16 v210, v47 offset:4640
	ds_write_b16_d16_hi v210, v47 offset:4656

.LBB0_144:
	global_load_dwordx4 v[164:167], v204, s[98:99] nt
	s_and_b64 vcc, exec, s[8:9]
	s_cbranch_vccnz .Lp1_skipE_l0
	global_load_dwordx4 v[196:199], v205, s[98:99] offset:256 nt
	global_load_dwordx4 v[200:203], v208, s[98:99] offset:256 nt
.Lp1_skipE_l0:
	s_add_u32 s98, s98, 0x12000
	s_addc_u32 s99, s99, 0
	global_load_dwordx4 v[168:171], v204, s[98:99] nt
	s_add_u32 s98, s98, 0x12000
	s_addc_u32 s99, s99, 0
	ds_read_b128 v[76:79], v141 offset:5120
	ds_read_b128 v[142:145], v141 offset:6144
	s_and_b64 vcc, exec, s[8:9]
	s_waitcnt vmcnt(8) lgkmcnt(1)
	v_mfma_f32_16x16x32_bf16 v[40:43], v[76:79], v[72:75], v[40:43]
	ds_read_b128 v[76:79], v141 offset:7168
	s_waitcnt lgkmcnt(1)
	v_mfma_f32_16x16x32_bf16 v[36:39], v[142:145], v[72:75], v[36:39]
	ds_read_b128 v[142:145], v141 offset:8192
	s_waitcnt lgkmcnt(1)
	v_mfma_f32_16x16x32_bf16 v[32:35], v[76:79], v[72:75], v[32:35]
	s_waitcnt lgkmcnt(0)
	v_mfma_f32_16x16x32_bf16 v[28:31], v[142:145], v[72:75], v[28:31]
	s_cbranch_vccnz .LBB0_146
	ds_read_b128 v[76:79], v141 offset:9216
	s_waitcnt lgkmcnt(0)
	v_mfma_f32_16x16x32_bf16 v[8:11], v[76:79], v[72:75], v[8:11]
.LBB0_146:
	global_load_dwordx4 v[172:175], v204, s[98:99] nt
	s_add_u32 s98, s98, 0x12000
	s_addc_u32 s99, s99, 0
	global_load_dwordx4 v[176:179], v204, s[98:99] nt
	s_add_u32 s98, s98, 0x12000
	s_addc_u32 s99, s99, 0
	ds_read_b128 v[72:75], v141 offset:10240
	ds_read_b128 v[76:79], v141 offset:11264
	s_and_b64 vcc, exec, s[8:9]
	s_waitcnt vmcnt(9) lgkmcnt(1)
	v_mfma_f32_16x16x32_bf16 v[40:43], v[72:75], v[68:71], v[40:43]
	ds_read_b128 v[72:75], v141 offset:12288
	s_waitcnt lgkmcnt(1)
	v_mfma_f32_16x16x32_bf16 v[36:39], v[76:79], v[68:71], v[36:39]
	ds_read_b128 v[76:79], v141 offset:13312
	s_waitcnt lgkmcnt(1)
	v_mfma_f32_16x16x32_bf16 v[32:35], v[72:75], v[68:71], v[32:35]
	s_waitcnt lgkmcnt(0)
	v_mfma_f32_16x16x32_bf16 v[28:31], v[76:79], v[68:71], v[28:31]
	s_cbranch_vccnz .LBB0_148
	ds_read_b128 v[72:75], v141 offset:14336
	s_waitcnt lgkmcnt(0)
	v_mfma_f32_16x16x32_bf16 v[8:11], v[72:75], v[68:71], v[8:11]
.LBB0_148:
	global_load_dwordx4 v[180:183], v204, s[98:99] nt
	s_add_u32 s98, s98, 0x12000
	s_addc_u32 s99, s99, 0
	global_load_dwordx4 v[184:187], v204, s[98:99] nt
	s_add_u32 s98, s98, 0x12000
	s_addc_u32 s99, s99, 0
	ds_read_b128 v[68:71], v141 offset:15360
	ds_read_b128 v[72:75], v141 offset:16384
	s_and_b64 vcc, exec, s[8:9]
	s_waitcnt vmcnt(10) lgkmcnt(1)
	v_mfma_f32_16x16x32_bf16 v[40:43], v[68:71], v[64:67], v[40:43]
	ds_read_b128 v[68:71], v141 offset:17408
	s_waitcnt lgkmcnt(1)
	v_mfma_f32_16x16x32_bf16 v[36:39], v[72:75], v[64:67], v[36:39]
	ds_read_b128 v[72:75], v141 offset:18432
	s_waitcnt lgkmcnt(1)
	v_mfma_f32_16x16x32_bf16 v[32:35], v[68:71], v[64:67], v[32:35]
	s_waitcnt lgkmcnt(0)
	v_mfma_f32_16x16x32_bf16 v[28:31], v[72:75], v[64:67], v[28:31]
	s_cbranch_vccnz .LBB0_150
	ds_read_b128 v[68:71], v141 offset:19456
	s_waitcnt lgkmcnt(0)
	v_mfma_f32_16x16x32_bf16 v[8:11], v[68:71], v[64:67], v[8:11]
.LBB0_150:
	global_load_dwordx4 v[188:191], v204, s[98:99] nt
	s_add_u32 s98, s98, 0x12000
	s_addc_u32 s99, s99, 0
	global_load_dwordx4 v[192:195], v204, s[98:99] nt
	ds_read_b128 v[64:67], v141 offset:20480
	ds_read_b128 v[68:71], v141 offset:21504
	s_and_b64 vcc, exec, s[8:9]
	s_waitcnt vmcnt(11) lgkmcnt(1)
	v_mfma_f32_16x16x32_bf16 v[40:43], v[64:67], v[60:63], v[40:43]
	ds_read_b128 v[64:67], v141 offset:22528
	s_waitcnt lgkmcnt(1)
	v_mfma_f32_16x16x32_bf16 v[36:39], v[68:71], v[60:63], v[36:39]
	ds_read_b128 v[68:71], v141 offset:23552
	s_waitcnt lgkmcnt(1)
	v_mfma_f32_16x16x32_bf16 v[32:35], v[64:67], v[60:63], v[32:35]
	s_waitcnt lgkmcnt(0)
	v_mfma_f32_16x16x32_bf16 v[28:31], v[68:71], v[60:63], v[28:31]
	s_cbranch_vccnz .LBB0_152
	ds_read_b128 v[64:67], v141 offset:24576
	s_waitcnt lgkmcnt(0)
	v_mfma_f32_16x16x32_bf16 v[8:11], v[64:67], v[60:63], v[8:11]

.LBB0_162:
	s_waitcnt vmcnt(0)
	v_add_u32_e32 v3, s21, v98
	v_add_u32_e32 v207, 0xa000, v206
	v_cvt_pk_bf16_f32 v44, v164, v168
	v_cvt_pk_bf16_f32 v45, v172, v176
	v_cvt_pk_bf16_f32 v46, v180, v184
	v_cvt_pk_bf16_f32 v47, v188, v192
	ds_write_b128 v207, v[44:47]
	v_cvt_pk_bf16_f32 v44, v165, v169
	v_cvt_pk_bf16_f32 v45, v173, v177
	v_cvt_pk_bf16_f32 v46, v181, v185
	v_cvt_pk_bf16_f32 v47, v189, v193
	ds_write_b128 v207, v[44:47] offset:16
	v_cvt_pk_bf16_f32 v44, v166, v170
	v_cvt_pk_bf16_f32 v45, v174, v178
	v_cvt_pk_bf16_f32 v46, v182, v186
	v_cvt_pk_bf16_f32 v47, v190, v194
	ds_write_b128 v207, v[44:47] offset:32
	v_cvt_pk_bf16_f32 v44, v167, v171
	v_cvt_pk_bf16_f32 v45, v175, v179
	v_cvt_pk_bf16_f32 v46, v183, v187
	v_cvt_pk_bf16_f32 v47, v191, v195
	ds_write_b128 v207, v[44:47] offset:48
	s_and_b64 vcc, exec, s[8:9]
	s_cbranch_vccnz .LBB0_164
	v_cvt_pk_bf16_f32 v44, v196, v197
	v_cvt_pk_bf16_f32 v45, v198, v199
	v_cvt_pk_bf16_f32 v46, v200, v201
	v_cvt_pk_bf16_f32 v47, v202, v203
	ds_write_b16 v209, v44 offset:45056
	ds_write_b16_d16_hi v209, v44 offset:45072
	ds_write_b16 v209, v45 offset:45088
	ds_write_b16_d16_hi v209, v45 offset:45104
	ds_write_b16 v209, v46 offset:45568
	ds_write_b16_d16_hi v209, v46 offset:45584
	ds_write_b16 v209, v47 offset:45600
	ds_write_b16_d16_hi v209, v47 offset:45616
